# attention: a wave skips band tiles that are fully masked for its rows (still stages and joins the barrier)
# speedup vs baseline: 1.0035x; 1.0035x over previous
.Lat2_band_3:
.Lat2_bandloop_4:
	s_sub_i32 s19, s45, s18
	s_add_i32 s6, s45, 3
	s_cmp_lt_u32 s6, s39
	s_cbranch_scc0 .Lat2_nodma_17
	s_add_i32 s4, s25, s16
	s_mov_b32 m0, s4
	s_lshl_b32 s5, s25, 1
	global_load_lds_dwordx4 v200, s[80:81]
	s_add_i32 s5, s5, s16
	s_add_i32 s5, s5, 0x8000
	s_mov_b32 m0, s5
	s_add_i32 s5, s5, 0x2000
	global_load_lds_dwordx4 v201, s[82:83]
	s_mov_b32 m0, s5
	s_nop 0
	global_load_lds_dwordx4 v202, s[82:83]
	s_add_u32 s80, s80, 0x10000
	s_addc_u32 s81, s81, 0
	s_add_u32 s82, s82, 0x10000
	s_addc_u32 s83, s83, 0
.Lat2_nodma_17:
	s_lshl_b32 s6, s19, 6
	s_lshl_b32 s7, s27, 5
	s_add_i32 s7, s7, 31
	s_cmp_gt_u32 s6, s7
	s_cbranch_scc1 .Lat2_allmasked_20
	v_add_u32_e32 v205, s59, v203
	ds_read_b128 v[116:119], v205 offset:0
	ds_read_b128 v[120:123], v205 offset:512
	ds_read_b128 v[124:127], v205 offset:2048
	ds_read_b128 v[128:131], v205 offset:2560
	ds_read_b128 v[132:135], v205 offset:4096
	ds_read_b128 v[136:139], v205 offset:4608
	ds_read_b128 v[140:143], v205 offset:6144
	ds_read_b128 v[144:147], v205 offset:6656
	s_lshl_b32 s7, s59, 1
	v_add_u32_e32 v206, s7, v204
	s_waitcnt lgkmcnt(6)
	v_mfma_f32_32x32x16_bf16 v[64:79], v[116:119], v[148:151], v[100:115]
	v_mfma_f32_32x32x16_bf16 v[80:95], v[120:123], v[148:151], v[100:115]
	s_waitcnt lgkmcnt(4)
	v_mfma_f32_32x32x16_bf16 v[64:79], v[124:127], v[152:155], v[64:79]
	v_mfma_f32_32x32x16_bf16 v[80:95], v[128:131], v[152:155], v[80:95]
	s_waitcnt lgkmcnt(2)
	v_mfma_f32_32x32x16_bf16 v[64:79], v[132:135], v[156:159], v[64:79]
	v_mfma_f32_32x32x16_bf16 v[80:95], v[136:139], v[156:159], v[80:95]
	s_waitcnt lgkmcnt(0)
	v_mfma_f32_32x32x16_bf16 v[64:79], v[140:143], v[160:163], v[64:79]
	v_mfma_f32_32x32x16_bf16 v[80:95], v[144:147], v[160:163], v[80:95]
	ds_read_b64_tr_b16 v[164:165], v206 offset:0
	ds_read_b64_tr_b16 v[166:167], v206 offset:512
	ds_read_b64_tr_b16 v[168:169], v206 offset:4096
	ds_read_b64_tr_b16 v[170:171], v206 offset:4608
	ds_read_b64_tr_b16 v[172:173], v206 offset:8192
	ds_read_b64_tr_b16 v[174:175], v206 offset:8704
	ds_read_b64_tr_b16 v[176:177], v206 offset:12288
	ds_read_b64_tr_b16 v[178:179], v206 offset:12800
	ds_read_b64_tr_b16 v[180:181], v206 offset:1024
	ds_read_b64_tr_b16 v[182:183], v206 offset:1536
	ds_read_b64_tr_b16 v[184:185], v206 offset:5120
	ds_read_b64_tr_b16 v[186:187], v206 offset:5632
	ds_read_b64_tr_b16 v[188:189], v206 offset:9216
	ds_read_b64_tr_b16 v[190:191], v206 offset:9728
	ds_read_b64_tr_b16 v[192:193], v206 offset:13312
	ds_read_b64_tr_b16 v[194:195], v206 offset:13824
	s_lshl_b32 s7, s19, 6
	v_subrev_u32_e32 v226, s7, v218
	v_cmp_gt_i32_e64 s[0:1], 0, v226
	v_cmp_gt_i32_e64 s[14:15], 1, v226
	v_cmp_gt_i32_e64 vcc, 2, v226
	v_cndmask_b32_e64 v64, v64, v219, s[0:1]
	v_cmp_gt_i32_e64 s[0:1], 3, v226
	v_cndmask_b32_e64 v65, v65, v219, s[14:15]
	v_cmp_gt_i32_e64 s[14:15], 8, v226
	v_cndmask_b32_e64 v66, v66, v219, vcc
	v_cmp_gt_i32_e64 vcc, 9, v226
	v_cndmask_b32_e64 v67, v67, v219, s[0:1]
	v_cmp_gt_i32_e64 s[0:1], 10, v226
	v_cndmask_b32_e64 v68, v68, v219, s[14:15]
	v_cmp_gt_i32_e64 s[14:15], 11, v226
	v_cndmask_b32_e64 v69, v69, v219, vcc
	v_cmp_gt_i32_e64 vcc, 16, v226
	v_cndmask_b32_e64 v70, v70, v219, s[0:1]
	v_cmp_gt_i32_e64 s[0:1], 17, v226
	v_cndmask_b32_e64 v71, v71, v219, s[14:15]
	v_cmp_gt_i32_e64 s[14:15], 18, v226
	v_cndmask_b32_e64 v72, v72, v219, vcc
	v_cmp_gt_i32_e64 vcc, 19, v226
	v_cndmask_b32_e64 v73, v73, v219, s[0:1]
	v_cmp_gt_i32_e64 s[0:1], 24, v226
	v_cndmask_b32_e64 v74, v74, v219, s[14:15]
	v_cmp_gt_i32_e64 s[14:15], 25, v226
	v_cndmask_b32_e64 v75, v75, v219, vcc
	v_cmp_gt_i32_e64 vcc, 26, v226
	v_cndmask_b32_e64 v76, v76, v219, s[0:1]
	v_cmp_gt_i32_e64 s[0:1], 27, v226
	v_cndmask_b32_e64 v77, v77, v219, s[14:15]
	v_cmp_gt_i32_e64 s[14:15], 32, v226
	v_cndmask_b32_e64 v78, v78, v219, vcc
	v_cmp_gt_i32_e64 vcc, 33, v226
	v_cndmask_b32_e64 v79, v79, v219, s[0:1]
	v_cmp_gt_i32_e64 s[0:1], 34, v226
	v_cndmask_b32_e64 v80, v80, v219, s[14:15]
	v_cmp_gt_i32_e64 s[14:15], 35, v226
	v_cndmask_b32_e64 v81, v81, v219, vcc
	v_cmp_gt_i32_e64 vcc, 40, v226
	v_cndmask_b32_e64 v82, v82, v219, s[0:1]
	v_cmp_gt_i32_e64 s[0:1], 41, v226
	v_cndmask_b32_e64 v83, v83, v219, s[14:15]
	v_cmp_gt_i32_e64 s[14:15], 42, v226
	v_cndmask_b32_e64 v84, v84, v219, vcc
	v_cmp_gt_i32_e64 vcc, 43, v226
	v_cndmask_b32_e64 v85, v85, v219, s[0:1]
	v_cmp_gt_i32_e64 s[0:1], 48, v226
	v_cndmask_b32_e64 v86, v86, v219, s[14:15]
	v_cmp_gt_i32_e64 s[14:15], 49, v226
	v_cndmask_b32_e64 v87, v87, v219, vcc
	v_cmp_gt_i32_e64 vcc, 50, v226
	v_cndmask_b32_e64 v88, v88, v219, s[0:1]
	v_cmp_gt_i32_e64 s[0:1], 51, v226
	v_cndmask_b32_e64 v89, v89, v219, s[14:15]
	v_cmp_gt_i32_e64 s[14:15], 56, v226
	v_cndmask_b32_e64 v90, v90, v219, vcc
	v_cmp_gt_i32_e64 vcc, 57, v226
	v_cndmask_b32_e64 v91, v91, v219, s[0:1]
	v_cmp_gt_i32_e64 s[0:1], 58, v226
	v_cndmask_b32_e64 v92, v92, v219, s[14:15]
	v_cmp_gt_i32_e64 s[14:15], 59, v226
	v_cndmask_b32_e64 v93, v93, v219, vcc
	s_nop 0
	v_cndmask_b32_e64 v94, v94, v219, s[0:1]
	s_nop 0
	v_cndmask_b32_e64 v95, v95, v219, s[14:15]
	v_max3_f32 v215, v64, v65, v80
	v_max3_f32 v216, v66, v67, v81
	v_max3_f32 v215, v215, v82, v83
	v_max3_f32 v216, v216, v68, v69
	v_max3_f32 v215, v215, v70, v71
	v_max3_f32 v216, v216, v84, v85
	v_max3_f32 v215, v215, v86, v87
	v_max3_f32 v216, v216, v72, v73
	v_max3_f32 v215, v215, v74, v75
	v_max3_f32 v216, v216, v88, v89
	v_max3_f32 v215, v215, v90, v91
	v_max3_f32 v216, v216, v76, v77
	v_max3_f32 v215, v215, v78, v79
	v_max3_f32 v216, v216, v92, v93
	v_max3_f32 v215, v215, v94, v95
	v_max_f32_e32 v214, v215, v216
	v_mov_b32_e32 v215, v214
	s_nop 1
	v_permlane32_swap_b32_e32 v214, v215
	s_nop 0
	v_max_f32_e32 v214, v214, v215
	v_cmp_lt_f32_e32 vcc, s62, v214
	s_cmp_lg_u64 vcc, 0
	s_cbranch_scc1 .Lat2_resc_18

.Lat2_allmasked_20:
	s_add_i32 s6, s45, 3
	s_cmp_lt_u32 s6, s39
	s_cbranch_scc1 .Lat2_w6_27
	s_cmp_eq_u32 s6, s39
	s_cbranch_scc1 .Lat2_w3_25
	s_waitcnt vmcnt(0)
	s_branch .Lat2_wd_26
